# MLA loop: slot-based K fragment addresses computed once per tile (4 adds instead of 8), duplicate Kr address add and 0+x adds removed
# baseline (speedup 1.0000x reference)
; #define SBAR() __builtin_amdgcn_sched_barrier(0)
; template <bool MLA>
; __device__ __forceinline__ void qkt_fin(f32x16& n0, f32x16& n1, const char* Ks, const char* Krs, const bf16x8* qr, int r32, int hi, const f32x16& cinit,
;                                         f32x16& p1, float alpha, float& l_reg, float ps0, bf16x8& pa2, bf16x8& pa3) {
;     ...
;     for (int s_ = 0; s_ < NSTEP; ++s_) {
;         const bool rope = s_ >= 8; const int d0 = rope ? s_ - 8 : s_; const int cb = (d0 * 16 + hi * 8) * 2;
;         const bf16x8 b0 = rope ? *reinterpret_cast<const bf16x8*>(Krs + KRSWZ(r32, cb)) : *reinterpret_cast<const bf16x8*>(Ks + KSWZ(r32, cb));
;         const bf16x8 b1 = rope ? *reinterpret_cast<const bf16x8*>(Krs + KRSWZ(32 + r32, cb)) : *reinterpret_cast<const bf16x8*>(Ks + KSWZ(32 + r32, cb));
;         if (s_ == 0) { n0 = __builtin_amdgcn_mfma_f32_32x32x16_bf16(b0, qr[0], cinit, 0, 0, 0); n1 = __builtin_amdgcn_mfma_f32_32x32x16_bf16(b1, qr[0], cinit, 0, 0, 0); }
;         else { n0 = __builtin_amdgcn_mfma_f32_32x32x16_bf16(b0, qr[s_], n0, 0, 0, 0); n1 = __builtin_amdgcn_mfma_f32_32x32x16_bf16(b1, qr[s_], n1, 0, 0, 0); }
;         if (s_ < 8) { p1[2 * s_] = __builtin_amdgcn_exp2f(p1[2 * s_]); p1[2 * s_ + 1] = __builtin_amdgcn_exp2f(p1[2 * s_ + 1]); ps += p1[2 * s_] + p1[2 * s_ + 1]; }
;         if (s_ == 4) PK4(p1, 0, pa2);
;         if (MLA && s_ == 8) { LFIN(); PK4(p1, 8, pa3); }
;         SBAR();
; template <int OFF> __device__ __forceinline__ s16x4 tr_read(int vb) {
;     s16x4 r; asm volatile("ds_read_b64_tr_b16 %0, %1 offset:%2" : "=&v"(r) : "v"(vb), "i"(OFF) : "memory"); return r;
; }
; template <int KS> __device__ __forceinline__ void pv_ks(f32x16* o, int vb, bf16x8 pa) {
;     const s16x4 l0 = tr_read<v_rd_off(0, KS, 0)>(vb), h0 = tr_read<v_rd_off(0, KS, 1)>(vb), l1 = tr_read<v_rd_off(1, KS, 0)>(vb), h1 = tr_read<v_rd_off(1, KS, 1)>(vb);
;     const s16x4 l2 = tr_read<v_rd_off(2, KS, 0)>(vb), h2 = tr_read<v_rd_off(2, KS, 1)>(vb), l3 = tr_read<v_rd_off(3, KS, 0)>(vb), h3 = tr_read<v_rd_off(3, KS, 1)>(vb);
;     asm volatile("s_waitcnt lgkmcnt(0)" ::: "memory"); SBAR();
;     ...
;     o[0] = __builtin_amdgcn_mfma_f32_32x32x16_bf16(pa, PK(l0, h0), o[0], 0, 0, 0);
;     o[1] = __builtin_amdgcn_mfma_f32_32x32x16_bf16(pa, PK(l1, h1), o[1], 0, 0, 0);
;     o[2] = __builtin_amdgcn_mfma_f32_32x32x16_bf16(pa, PK(l2, h2), o[2], 0, 0, 0);
.LBB0_459:
	s_lshl_b32 s15, s24, 14
	s_add_i32 s10, s15, 0
	v_add_u32_e32 v236, s10, v224
	v_add_u32_e32 v237, s10, v225
	v_add_u32_e32 v238, s10, v226
	v_add_u32_e32 v239, s10, v227
	ds_read_b128 v[96:99], v236
	ds_read_b128 v[202:205], v236 offset:8192
	v_exp_f32_e32 v188, v80
	v_exp_f32_e32 v189, v81
	s_lshl_b32 s11, s24, 13
	s_waitcnt lgkmcnt(0)
	v_mfma_f32_32x32x16_bf16 v[112:127], v[96:99], v[172:175], v[64:79]
	s_sub_i32 s6, s10, s11
	v_add_f32_e32 v80, v189, v188
	v_add_f32_e32 v80, v80, v200
	v_mfma_f32_32x32x16_bf16 v[96:111], v[202:205], v[172:175], v[64:79]
	ds_read_b128 v[200:203], v237
	ds_read_b128 v[242:245], v237 offset:8192
	v_exp_f32_e32 v190, v82
	v_exp_f32_e32 v191, v83
	s_waitcnt lgkmcnt(0)
	v_mfma_f32_32x32x16_bf16 v[112:127], v[200:203], v[168:171], v[112:127]
	v_add_f32_e32 v81, v191, v190
	v_add_f32_e32 v204, v81, v80
	v_mfma_f32_32x32x16_bf16 v[96:111], v[242:245], v[168:171], v[96:111]
	ds_read_b128 v[80:83], v238
	ds_read_b128 v[200:203], v238 offset:8192
	v_exp_f32_e32 v205, v84
	v_exp_f32_e32 v206, v85
	s_waitcnt lgkmcnt(0)
	v_mfma_f32_32x32x16_bf16 v[112:127], v[80:83], v[164:167], v[112:127]
	v_add_f32_e32 v80, v206, v205
	v_add_f32_e32 v84, v80, v204
	v_mfma_f32_32x32x16_bf16 v[96:111], v[200:203], v[164:167], v[96:111]
	ds_read_b128 v[80:83], v239
	ds_read_b128 v[200:203], v239 offset:8192
	v_exp_f32_e32 v204, v86
	v_exp_f32_e32 v207, v87
	s_waitcnt lgkmcnt(0)
	v_mfma_f32_32x32x16_bf16 v[112:127], v[80:83], v[160:163], v[112:127]
	v_add_f32_e32 v80, v207, v204
	v_add_f32_e32 v208, v80, v84
	v_mfma_f32_32x32x16_bf16 v[96:111], v[200:203], v[160:163], v[96:111]
	ds_read_b128 v[80:83], v236 offset:128
	ds_read_b128 v[84:87], v236 offset:8320
	v_exp_f32_e32 v209, v88
	v_exp_f32_e32 v243, v89
	s_waitcnt lgkmcnt(0)
	v_mfma_f32_32x32x16_bf16 v[112:127], v[80:83], v[156:159], v[112:127]
	v_add_f32_e32 v80, v243, v209
	v_add_f32_e32 v88, v80, v208
	v_cvt_pk_bf16_f32 v80, v188, v189
	v_cvt_pk_bf16_f32 v81, v190, v191
	v_cvt_pk_bf16_f32 v82, v205, v206
	v_cvt_pk_bf16_f32 v83, v204, v207
	v_mfma_f32_32x32x16_bf16 v[96:111], v[84:87], v[156:159], v[96:111]
	v_permlane32_swap_b32_e32 v80, v82
	v_permlane32_swap_b32_e32 v81, v83
	ds_read_b128 v[84:87], v237 offset:128
	ds_read_b128 v[200:203], v237 offset:8320
	v_exp_f32_e32 v188, v90
	v_exp_f32_e32 v189, v91
	s_waitcnt lgkmcnt(0)
	v_mfma_f32_32x32x16_bf16 v[112:127], v[84:87], v[152:155], v[112:127]
	v_add_f32_e32 v84, v189, v188
	v_add_f32_e32 v190, v84, v88
	v_mfma_f32_32x32x16_bf16 v[96:111], v[200:203], v[152:155], v[96:111]
	ds_read_b128 v[84:87], v238 offset:128
	ds_read_b128 v[88:91], v238 offset:8320
	v_exp_f32_e32 v92, v92
	v_exp_f32_e32 v93, v93
	s_waitcnt lgkmcnt(0)
	v_mfma_f32_32x32x16_bf16 v[112:127], v[84:87], v[148:151], v[112:127]
	v_add_f32_e32 v84, v93, v92
	v_add_f32_e32 v190, v84, v190
	v_mfma_f32_32x32x16_bf16 v[96:111], v[88:91], v[148:151], v[96:111]
	ds_read_b128 v[84:87], v239 offset:128
	ds_read_b128 v[88:91], v239 offset:8320
	v_exp_f32_e32 v94, v94
	v_exp_f32_e32 v95, v95
	s_waitcnt lgkmcnt(0)
	v_mfma_f32_32x32x16_bf16 v[112:127], v[84:87], v[144:147], v[112:127]
	v_add_f32_e32 v84, v95, v94
	v_add_f32_e32 v241, v84, v190
	v_mfma_f32_32x32x16_bf16 v[96:111], v[88:91], v[144:147], v[96:111]
	v_add_u32_e32 v84, s6, v232
	ds_read_b128 v[88:91], v84 offset:53248
	ds_read_b128 v[84:87], v84 offset:49152
	v_mov_b32_e32 v242, v241
	s_nop 1
	v_permlane32_swap_b32_e32 v241, v242
	s_waitcnt lgkmcnt(0)
	v_mfma_f32_32x32x16_bf16 v[112:127], v[84:87], v[140:143], v[112:127]
	v_cvt_pk_bf16_f32 v84, v209, v243
	v_cvt_pk_bf16_f32 v85, v188, v189
	v_cvt_pk_bf16_f32 v86, v92, v93
	v_cvt_pk_bf16_f32 v87, v94, v95
	s_nop 0
	v_permlane32_swap_b32_e32 v84, v86
	v_mfma_f32_32x32x16_bf16 v[96:111], v[88:91], v[140:143], v[96:111]
	v_permlane32_swap_b32_e32 v85, v87
	v_add_u32_e32 v189, s6, v233
	v_add_u32_e32 v190, s6, v234
	ds_read_b128 v[88:91], v189 offset:49152
	ds_read_b128 v[228:231], v189 offset:53248
	ds_read_b128 v[92:95], v190 offset:49152
	ds_read_b128 v[236:239], v190 offset:53248
	v_add_u32_e32 v191, s6, v235
	s_waitcnt lgkmcnt(3)
	v_mfma_f32_32x32x16_bf16 v[112:127], v[88:91], v[136:139], v[112:127]
	s_waitcnt lgkmcnt(2)
	v_mfma_f32_32x32x16_bf16 v[96:111], v[228:231], v[136:139], v[96:111]
	ds_read_b128 v[88:91], v191 offset:49152
	ds_read_b128 v[228:231], v191 offset:53248
	s_waitcnt lgkmcnt(3)
	v_mfma_f32_32x32x16_bf16 v[112:127], v[92:95], v[132:135], v[112:127]
	s_waitcnt lgkmcnt(2)
	v_mfma_f32_32x32x16_bf16 v[96:111], v[236:239], v[132:135], v[96:111]
	s_waitcnt lgkmcnt(1)
	v_mfma_f32_32x32x16_bf16 v[112:127], v[88:91], v[128:131], v[112:127]
	s_waitcnt lgkmcnt(0)
	v_mfma_f32_32x32x16_bf16 v[96:111], v[228:231], v[128:131], v[96:111]
	s_lshl_b32 s21, s21, 14
	v_add_u32_e32 v188, s21, v210
	ds_read_b64_tr_b16 v[88:89], v188 offset:0
	ds_read_b64_tr_b16 v[90:91], v188 offset:0x800
	ds_read_b64_tr_b16 v[92:93], v188 offset:0x200
	ds_read_b64_tr_b16 v[94:95], v188 offset:0xa00
	ds_read_b64_tr_b16 v[200:201], v188 offset:0x400
	ds_read_b64_tr_b16 v[202:203], v188 offset:0xc00
	ds_read_b64_tr_b16 v[204:205], v188 offset:0x600
	ds_read_b64_tr_b16 v[206:207], v188 offset:0xe00
	ds_read_b64_tr_b16 v[228:229], v188 offset:0x1000
	ds_read_b64_tr_b16 v[230:231], v188 offset:0x1800
	ds_read_b64_tr_b16 v[236:237], v188 offset:0x1200
	ds_read_b64_tr_b16 v[238:239], v188 offset:0x1a00
	v_max_f32_e32 v189, v113, v113
	v_max_f32_e32 v190, v112, v112
	v_max_f32_e32 v189, v190, v189
	v_max3_f32 v189, v189, v114, v115
	v_max3_f32 v189, v189, v116, v117
	v_max3_f32 v189, v189, v118, v119
	v_max3_f32 v189, v189, v120, v121
	v_max3_f32 v189, v189, v122, v123
	v_max3_f32 v189, v189, v124, v125
	v_max3_f32 v189, v189, v126, v127
	s_waitcnt lgkmcnt(4)
; #define SBAR() __builtin_amdgcn_sched_barrier(0)
; template <bool FIRST>
; __device__ __forceinline__ void partialSM_mla(f32x16& p0, f32x16& p1, float& m_reg, f32x16& negm, float& alpha) {
;     constexpr float THRL = THR * LOG2E;
;     float pmax = p0[0];
; #pragma unroll
;     for (int r = 1; r < 16; ++r) pmax = fmaxf(pmax, p0[r]);
; #pragma unroll
;     for (int r = 0; r < 16; ++r) pmax = fmaxf(pmax, p1[r]);
;     { auto rr = __builtin_amdgcn_permlane32_swap(__float_as_uint(pmax), __float_as_uint(pmax), false, false);
;       pmax = fmaxf(__uint_as_float(rr[0]), __uint_as_float(rr[1])); }
;     if (!FIRST && __builtin_expect(__all(pmax <= THRL), 1)) { alpha = 1.f; }
;     else { const float dl = FIRST ? pmax : fmaxf(pmax, 0.f); m_reg += dl; alpha = FIRST ? 1.f : __builtin_amdgcn_exp2f(-dl);
; #pragma unroll
;         for (int r = 0; r < 16; ++r) { p0[r] -= dl; p1[r] -= dl; }
; #pragma unroll
;         for (int r = 0; r < 16; ++r) negm[r] = -m_reg;
;         asm volatile("" : "+v"(negm)); }
; #pragma unroll
;     for (int r = 0; r < 16; ++r) p0[r] = __builtin_amdgcn_exp2f(p0[r]);
; }
; template <int OFF> __device__ __forceinline__ s16x4 tr_read(int vb) {
;     s16x4 r; asm volatile("ds_read_b64_tr_b16 %0, %1 offset:%2" : "=&v"(r) : "v"(vb), "i"(OFF) : "memory"); return r;
; }
; template <int KS> __device__ __forceinline__ void pv_ks(f32x16* o, int vb, bf16x8 pa) {
;     const s16x4 l0 = tr_read<v_rd_off(0, KS, 0)>(vb), h0 = tr_read<v_rd_off(0, KS, 1)>(vb), l1 = tr_read<v_rd_off(1, KS, 0)>(vb), h1 = tr_read<v_rd_off(1, KS, 1)>(vb);
;     const s16x4 l2 = tr_read<v_rd_off(2, KS, 0)>(vb), h2 = tr_read<v_rd_off(2, KS, 1)>(vb), l3 = tr_read<v_rd_off(3, KS, 0)>(vb), h3 = tr_read<v_rd_off(3, KS, 1)>(vb);
;     asm volatile("s_waitcnt lgkmcnt(0)" ::: "memory"); SBAR();
;     ...
;     o[0] = __builtin_amdgcn_mfma_f32_32x32x16_bf16(pa, PK(l0, h0), o[0], 0, 0, 0);
;     o[1] = __builtin_amdgcn_mfma_f32_32x32x16_bf16(pa, PK(l1, h1), o[1], 0, 0, 0);
;     o[2] = __builtin_amdgcn_mfma_f32_32x32x16_bf16(pa, PK(l2, h2), o[2], 0, 0, 0);
;     o[3] = __builtin_amdgcn_mfma_f32_32x32x16_bf16(pa, PK(l3, h3), o[3], 0, 0, 0);
	v_mfma_f32_32x32x16_bf16 v[0:15], v[180:183], v[88:91], v[0:15]
	ds_read_b64_tr_b16 v[88:89], v188 offset:0x1400
	ds_read_b64_tr_b16 v[90:91], v188 offset:0x1c00
	v_max3_f32 v189, v189, v96, v97
	v_max3_f32 v189, v189, v98, v99
	v_mfma_f32_32x32x16_bf16 v[48:63], v[180:183], v[92:95], v[48:63]
	ds_read_b64_tr_b16 v[92:93], v188 offset:0x1600
	ds_read_b64_tr_b16 v[94:95], v188 offset:0x1e00
	v_max3_f32 v189, v189, v100, v101
	v_max3_f32 v189, v189, v102, v103
	v_mfma_f32_32x32x16_bf16 v[32:47], v[180:183], v[200:203], v[32:47]
	v_max3_f32 v189, v189, v104, v105
	v_max3_f32 v189, v189, v106, v107
	v_mfma_f32_32x32x16_bf16 v[16:31], v[180:183], v[204:207], v[16:31]
	ds_read_b64_tr_b16 v[200:201], v188 offset:0x2000
	ds_read_b64_tr_b16 v[202:203], v188 offset:0x2800
	ds_read_b64_tr_b16 v[204:205], v188 offset:0x2200
	ds_read_b64_tr_b16 v[206:207], v188 offset:0x2a00
	v_max3_f32 v189, v189, v108, v109
	v_max3_f32 v189, v189, v110, v111
	v_mov_b32_e32 v190, v189
	s_waitcnt lgkmcnt(4)
	v_mfma_f32_32x32x16_bf16 v[0:15], v[176:179], v[228:231], v[0:15]
	ds_read_b64_tr_b16 v[228:229], v188 offset:0x2400
	ds_read_b64_tr_b16 v[230:231], v188 offset:0x2c00
	v_permlane32_swap_b32_e32 v189, v190
	v_mfma_f32_32x32x16_bf16 v[48:63], v[176:179], v[236:239], v[48:63]
	ds_read_b64_tr_b16 v[236:237], v188 offset:0x2600
	ds_read_b64_tr_b16 v[238:239], v188 offset:0x2e00
	v_max_f32_e32 v190, v190, v190
	v_max_f32_e32 v189, v189, v189
	v_max_f32_e32 v189, v189, v190
	v_mfma_f32_32x32x16_bf16 v[32:47], v[176:179], v[88:91], v[32:47]
	v_cmp_ge_f32_e32 vcc, s90, v189
	s_cmp_eq_u64 vcc, exec
	v_mfma_f32_32x32x16_bf16 v[16:31], v[176:179], v[92:95], v[16:31]
	ds_read_b64_tr_b16 v[88:89], v188 offset:0x3000
	ds_read_b64_tr_b16 v[90:91], v188 offset:0x3800
	ds_read_b64_tr_b16 v[92:93], v188 offset:0x3200
	ds_read_b64_tr_b16 v[94:95], v188 offset:0x3a00
	s_cbranch_scc0 .LBB0_482
	v_mov_b32_e32 v244, 1.0
.LBB0_461:
	v_exp_f32_e32 v112, v112
	v_exp_f32_e32 v113, v113
	v_exp_f32_e32 v114, v114
	v_exp_f32_e32 v115, v115
	s_waitcnt lgkmcnt(4)
	v_mfma_f32_32x32x16_bf16 v[0:15], v[80:83], v[200:203], v[0:15]
	ds_read_b64_tr_b16 v[200:201], v188 offset:0x3400
	ds_read_b64_tr_b16 v[202:203], v188 offset:0x3c00
	v_exp_f32_e32 v116, v116
	v_exp_f32_e32 v117, v117
	v_cvt_pk_bf16_f32 v180, v112, v113
	v_mfma_f32_32x32x16_bf16 v[48:63], v[80:83], v[204:207], v[48:63]
	ds_read_b64_tr_b16 v[204:205], v188 offset:0x3600
	ds_read_b64_tr_b16 v[206:207], v188 offset:0x3e00
	v_exp_f32_e32 v118, v118
	v_exp_f32_e32 v119, v119
	v_cvt_pk_bf16_f32 v181, v114, v115
	v_mfma_f32_32x32x16_bf16 v[32:47], v[80:83], v[228:231], v[32:47]
	v_exp_f32_e32 v120, v120
	v_exp_f32_e32 v121, v121
	v_cvt_pk_bf16_f32 v182, v116, v117
	v_mfma_f32_32x32x16_bf16 v[16:31], v[80:83], v[236:239], v[16:31]
	v_exp_f32_e32 v122, v122
	v_exp_f32_e32 v123, v123
	v_cvt_pk_bf16_f32 v183, v118, v119
	v_add_f32_e32 v191, v113, v112
	s_waitcnt lgkmcnt(0)
	v_mfma_f32_32x32x16_bf16 v[0:15], v[84:87], v[88:91], v[0:15]
	v_exp_f32_e32 v124, v124
	v_exp_f32_e32 v125, v125
	v_permlane32_swap_b32_e32 v180, v182
	v_add_f32_e32 v191, v114, v191
	v_add_f32_e32 v191, v115, v191
	v_mfma_f32_32x32x16_bf16 v[48:63], v[84:87], v[92:95], v[48:63]
	v_exp_f32_e32 v126, v126
	v_exp_f32_e32 v127, v127
	v_permlane32_swap_b32_e32 v181, v183
	v_add_f32_e32 v191, v116, v191
	v_add_f32_e32 v191, v117, v191
	v_mfma_f32_32x32x16_bf16 v[32:47], v[84:87], v[200:203], v[32:47]
	v_cvt_pk_bf16_f32 v176, v120, v121
	v_cvt_pk_bf16_f32 v177, v122, v123
	v_cvt_pk_bf16_f32 v178, v124, v125
	v_add_f32_e32 v191, v118, v191
	v_add_f32_e32 v191, v119, v191
	v_add_f32_e32 v191, v120, v191
	v_mfma_f32_32x32x16_bf16 v[16:31], v[84:87], v[204:207], v[16:31]
	v_cvt_pk_bf16_f32 v179, v126, v127
	v_add_f32_e32 v191, v121, v191
	v_add_f32_e32 v191, v122, v191
	v_add_f32_e32 v191, v123, v191
	v_add_f32_e32 v191, v124, v191
	v_permlane32_swap_b32_e32 v176, v178
	v_add_f32_e32 v191, v125, v191
	v_permlane32_swap_b32_e32 v177, v179
	v_add_f32_e32 v191, v126, v191
	v_add_f32_e32 v84, v127, v191
	v_cmp_gt_f32_e32 vcc, 1.0, v244
	s_cbranch_vccz .LBB0_465
	s_and_saveexec_b64 s[6:7], s[36:37]
	ds_write_b32 v211, v244 offset:128
	s_or_b64 exec, exec, s[6:7]
	s_waitcnt lgkmcnt(0)
	v_add_u32_e32 v124, v193, v184
	ds_read_b128 v[112:115], v124 offset:224
	ds_read_b128 v[116:119], v124 offset:192
	ds_read_b128 v[120:123], v124 offset:160
	ds_read_b128 v[124:127], v124 offset:128
	s_waitcnt lgkmcnt(0)
	v_pk_mul_f32 v[12:13], v[12:13], v[112:113]
	v_pk_mul_f32 v[8:9], v[8:9], v[116:117]
	v_pk_mul_f32 v[4:5], v[4:5], v[120:121]
	v_pk_mul_f32 v[14:15], v[14:15], v[114:115]
	v_pk_mul_f32 v[10:11], v[10:11], v[118:119]
	v_pk_mul_f32 v[6:7], v[6:7], v[122:123]
	v_pk_mul_f32 v[2:3], v[2:3], v[126:127]
	v_pk_mul_f32 v[0:1], v[0:1], v[124:125]
	v_pk_mul_f32 v[60:61], v[60:61], v[112:113]
	v_pk_mul_f32 v[56:57], v[56:57], v[116:117]
	v_pk_mul_f32 v[52:53], v[52:53], v[120:121]
	v_pk_mul_f32 v[62:63], v[62:63], v[114:115]
	v_pk_mul_f32 v[58:59], v[58:59], v[118:119]
	v_pk_mul_f32 v[54:55], v[54:55], v[122:123]
	v_pk_mul_f32 v[50:51], v[50:51], v[126:127]
	v_pk_mul_f32 v[48:49], v[48:49], v[124:125]
	v_pk_mul_f32 v[44:45], v[44:45], v[112:113]
	v_pk_mul_f32 v[40:41], v[40:41], v[116:117]
	v_pk_mul_f32 v[36:37], v[36:37], v[120:121]
	v_pk_mul_f32 v[46:47], v[46:47], v[114:115]
	v_pk_mul_f32 v[42:43], v[42:43], v[118:119]
	v_pk_mul_f32 v[38:39], v[38:39], v[122:123]
	v_pk_mul_f32 v[34:35], v[34:35], v[126:127]
	v_pk_mul_f32 v[32:33], v[32:33], v[124:125]
	v_pk_mul_f32 v[28:29], v[28:29], v[112:113]
	v_pk_mul_f32 v[24:25], v[24:25], v[116:117]
	v_pk_mul_f32 v[20:21], v[20:21], v[120:121]
	v_pk_mul_f32 v[30:31], v[30:31], v[114:115]
	v_pk_mul_f32 v[26:27], v[26:27], v[118:119]
	v_pk_mul_f32 v[22:23], v[22:23], v[122:123]
	v_pk_mul_f32 v[18:19], v[18:19], v[126:127]
	v_pk_mul_f32 v[16:17], v[16:17], v[124:125]

; #define SBAR() __builtin_amdgcn_sched_barrier(0)
; #define LFIN() do { auto rr = __builtin_amdgcn_permlane32_swap(__float_as_uint(ps), __float_as_uint(ps), false, false); \
;     ps = __uint_as_float(rr[0]) + __uint_as_float(rr[1]); l_reg = l_reg * alpha + ps; } while (0)
; template <bool MLA>
; __device__ __forceinline__ void qkt_fin(f32x16& n0, f32x16& n1, const char* Ks, const char* Krs, const bf16x8* qr, int r32, int hi, const f32x16& cinit,
;                                         f32x16& p1, float alpha, float& l_reg, float ps0, bf16x8& pa2, bf16x8& pa3) {
;     ...
;     for (int s_ = 0; s_ < NSTEP; ++s_) {
;         const bool rope = s_ >= 8; const int d0 = rope ? s_ - 8 : s_; const int cb = (d0 * 16 + hi * 8) * 2;
;         const bf16x8 b0 = rope ? *reinterpret_cast<const bf16x8*>(Krs + KRSWZ(r32, cb)) : *reinterpret_cast<const bf16x8*>(Ks + KSWZ(r32, cb));
;         const bf16x8 b1 = rope ? *reinterpret_cast<const bf16x8*>(Krs + KRSWZ(32 + r32, cb)) : *reinterpret_cast<const bf16x8*>(Ks + KSWZ(32 + r32, cb));
;         if (s_ == 0) { n0 = __builtin_amdgcn_mfma_f32_32x32x16_bf16(b0, qr[0], cinit, 0, 0, 0); n1 = __builtin_amdgcn_mfma_f32_32x32x16_bf16(b1, qr[0], cinit, 0, 0, 0); }
;         else { n0 = __builtin_amdgcn_mfma_f32_32x32x16_bf16(b0, qr[s_], n0, 0, 0, 0); n1 = __builtin_amdgcn_mfma_f32_32x32x16_bf16(b1, qr[s_], n1, 0, 0, 0); }
;         if (s_ < 8) { p1[2 * s_] = __builtin_amdgcn_exp2f(p1[2 * s_]); p1[2 * s_ + 1] = __builtin_amdgcn_exp2f(p1[2 * s_ + 1]); ps += p1[2 * s_] + p1[2 * s_ + 1]; }
;         if (s_ == 4) PK4(p1, 0, pa2);
;         if (MLA && s_ == 8) { LFIN(); PK4(p1, 8, pa3); }
;         SBAR();
.LBB0_467:
	s_add_u32 s10, s84, 0x1eec0100
	s_addc_u32 s11, s85, 0
	s_add_i32 s21, s12, s21
	s_mov_b32 m0, s21
	s_nop 0
	global_load_lds_dwordx4 v198, s[10:11]
	s_add_u32 s10, s84, 0x1eee0100
	s_addc_u32 s11, s85, 0
	s_add_i32 m0, s21, 0x2000
	s_nop 0
	global_load_lds_dwordx4 v198, s[10:11]
	s_lshl_b32 s21, s13, 14
	s_add_i32 s24, s21, 0
	v_add_u32_e32 v236, s24, v224
	v_add_u32_e32 v237, s24, v225
	v_add_u32_e32 v238, s24, v226
	v_add_u32_e32 v239, s24, v227
	ds_read_b128 v[80:83], v236
	ds_read_b128 v[246:249], v236 offset:8192
	v_exp_f32_e32 v206, v96
	v_exp_f32_e32 v207, v97
	s_lshl_b32 s25, s13, 13
	s_waitcnt lgkmcnt(0)
	v_mfma_f32_32x32x16_bf16 v[112:127], v[80:83], v[172:175], v[64:79]
	s_sub_i32 s10, s24, s25
	v_add_f32_e32 v80, v207, v206
	v_add_f32_e32 v96, v80, v84
	v_mfma_f32_32x32x16_bf16 v[80:95], v[246:249], v[172:175], v[64:79]
	ds_read_b128 v[246:249], v237
	ds_read_b128 v[188:191], v237 offset:8192
	v_exp_f32_e32 v208, v98
	v_exp_f32_e32 v209, v99
	s_waitcnt lgkmcnt(0)
	v_mfma_f32_32x32x16_bf16 v[112:127], v[246:249], v[168:171], v[112:127]
	v_add_f32_e32 v97, v209, v208
	v_add_f32_e32 v243, v97, v96
	v_mfma_f32_32x32x16_bf16 v[80:95], v[188:191], v[168:171], v[80:95]
	ds_read_b128 v[96:99], v238
	ds_read_b128 v[188:191], v238 offset:8192
	v_exp_f32_e32 v245, v100
	v_exp_f32_e32 v246, v101
	s_waitcnt lgkmcnt(0)
	v_mfma_f32_32x32x16_bf16 v[112:127], v[96:99], v[164:167], v[112:127]
	v_add_f32_e32 v96, v246, v245
	v_add_f32_e32 v100, v96, v243
	v_mfma_f32_32x32x16_bf16 v[80:95], v[188:191], v[164:167], v[80:95]
	ds_read_b128 v[96:99], v239
	ds_read_b128 v[188:191], v239 offset:8192
	v_exp_f32_e32 v243, v102
	v_exp_f32_e32 v247, v103
	s_waitcnt lgkmcnt(0)
	v_mfma_f32_32x32x16_bf16 v[112:127], v[96:99], v[160:163], v[112:127]
	v_add_f32_e32 v96, v247, v243
	v_add_f32_e32 v248, v96, v100
	v_mfma_f32_32x32x16_bf16 v[80:95], v[188:191], v[160:163], v[80:95]
	ds_read_b128 v[96:99], v236 offset:128
	ds_read_b128 v[100:103], v236 offset:8320
	v_exp_f32_e32 v249, v104
	v_exp_f32_e32 v186, v105
	s_waitcnt lgkmcnt(0)
	v_mfma_f32_32x32x16_bf16 v[112:127], v[96:99], v[156:159], v[112:127]
	v_add_f32_e32 v96, v186, v249
	v_add_f32_e32 v104, v96, v248
	v_cvt_pk_bf16_f32 v96, v206, v207
	v_cvt_pk_bf16_f32 v97, v208, v209
	v_cvt_pk_bf16_f32 v98, v245, v246
	v_cvt_pk_bf16_f32 v99, v243, v247
	v_mfma_f32_32x32x16_bf16 v[80:95], v[100:103], v[156:159], v[80:95]
	v_permlane32_swap_b32_e32 v96, v98
	v_permlane32_swap_b32_e32 v97, v99
	ds_read_b128 v[100:103], v237 offset:128
	ds_read_b128 v[188:191], v237 offset:8320
	v_exp_f32_e32 v206, v106
	v_exp_f32_e32 v207, v107
	s_waitcnt lgkmcnt(0)
	v_mfma_f32_32x32x16_bf16 v[112:127], v[100:103], v[152:155], v[112:127]
	v_add_f32_e32 v100, v207, v206
	v_add_f32_e32 v208, v100, v104
	v_mfma_f32_32x32x16_bf16 v[80:95], v[188:191], v[152:155], v[80:95]
	ds_read_b128 v[100:103], v238 offset:128
	ds_read_b128 v[104:107], v238 offset:8320
	v_exp_f32_e32 v188, v108
	v_exp_f32_e32 v189, v109
	s_waitcnt lgkmcnt(0)
	v_mfma_f32_32x32x16_bf16 v[112:127], v[100:103], v[148:151], v[112:127]
	v_add_f32_e32 v100, v189, v188
	v_add_f32_e32 v108, v100, v208
	v_mfma_f32_32x32x16_bf16 v[80:95], v[104:107], v[148:151], v[80:95]
	ds_read_b128 v[100:103], v239 offset:128
	ds_read_b128 v[104:107], v239 offset:8320
	v_exp_f32_e32 v110, v110
	v_exp_f32_e32 v111, v111
	s_waitcnt lgkmcnt(0)
	v_mfma_f32_32x32x16_bf16 v[112:127], v[100:103], v[144:147], v[112:127]
	v_add_f32_e32 v100, v111, v110
	v_add_f32_e32 v100, v100, v108
	v_mfma_f32_32x32x16_bf16 v[80:95], v[104:107], v[144:147], v[80:95]
	v_add_u32_e32 v101, s10, v232
	ds_read_b128 v[102:105], v101 offset:49152
	ds_read_b128 v[106:109], v101 offset:53248
	v_mov_b32_e32 v101, v100
	s_nop 1
	v_permlane32_swap_b32_e32 v100, v101
	s_waitcnt lgkmcnt(0)
	v_mfma_f32_32x32x16_bf16 v[112:127], v[102:105], v[140:143], v[112:127]
	v_cvt_pk_bf16_f32 v102, v249, v186
	v_cvt_pk_bf16_f32 v103, v206, v207
	v_cvt_pk_bf16_f32 v104, v188, v189
	v_cvt_pk_bf16_f32 v105, v110, v111
	s_nop 0
	v_permlane32_swap_b32_e32 v102, v104
	v_mfma_f32_32x32x16_bf16 v[80:95], v[106:109], v[140:143], v[80:95]
	v_permlane32_swap_b32_e32 v103, v105
	v_add_u32_e32 v110, s10, v233
	v_add_u32_e32 v111, s10, v234
	ds_read_b128 v[106:109], v110 offset:49152
	ds_read_b128 v[228:231], v110 offset:53248
	ds_read_b128 v[188:191], v111 offset:49152
	ds_read_b128 v[236:239], v111 offset:53248
	v_add_u32_e32 v245, s10, v235
	s_waitcnt lgkmcnt(3)
	v_mfma_f32_32x32x16_bf16 v[112:127], v[106:109], v[136:139], v[112:127]
	s_waitcnt lgkmcnt(2)
	v_mfma_f32_32x32x16_bf16 v[80:95], v[228:231], v[136:139], v[80:95]
	ds_read_b128 v[106:109], v245 offset:49152
	ds_read_b128 v[228:231], v245 offset:53248
	s_waitcnt lgkmcnt(3)
	v_mfma_f32_32x32x16_bf16 v[112:127], v[188:191], v[132:135], v[112:127]
	s_waitcnt lgkmcnt(2)
	v_mfma_f32_32x32x16_bf16 v[80:95], v[236:239], v[132:135], v[80:95]
	s_waitcnt lgkmcnt(1)
	v_mfma_f32_32x32x16_bf16 v[112:127], v[106:109], v[128:131], v[112:127]
	s_waitcnt lgkmcnt(0)
	v_mfma_f32_32x32x16_bf16 v[80:95], v[228:231], v[128:131], v[80:95]
	v_add_u32_e32 v110, s15, v210
	ds_read_b64_tr_b16 v[106:107], v110 offset:0
	ds_read_b64_tr_b16 v[108:109], v110 offset:0x800
	ds_read_b64_tr_b16 v[188:189], v110 offset:0x200
	ds_read_b64_tr_b16 v[190:191], v110 offset:0xa00
	ds_read_b64_tr_b16 v[246:247], v110 offset:0x400
	ds_read_b64_tr_b16 v[248:249], v110 offset:0xc00
	ds_read_b64_tr_b16 v[206:207], v110 offset:0x600
	ds_read_b64_tr_b16 v[208:209], v110 offset:0xe00
	ds_read_b64_tr_b16 v[228:229], v110 offset:0x1000
	ds_read_b64_tr_b16 v[230:231], v110 offset:0x1800
	ds_read_b64_tr_b16 v[236:237], v110 offset:0x1200
	ds_read_b64_tr_b16 v[238:239], v110 offset:0x1a00
	v_max_f32_e32 v111, v113, v113
	v_max_f32_e32 v245, v112, v112
	v_max_f32_e32 v111, v245, v111
	v_max3_f32 v111, v111, v114, v115
	v_max3_f32 v111, v111, v116, v117
	v_max3_f32 v111, v111, v118, v119
	v_max3_f32 v111, v111, v120, v121
	v_max3_f32 v111, v111, v122, v123
	v_max3_f32 v111, v111, v124, v125
	v_max3_f32 v111, v111, v126, v127
	s_waitcnt lgkmcnt(4)
; #define SBAR() __builtin_amdgcn_sched_barrier(0)
; template <bool FIRST>
; __device__ __forceinline__ void partialSM_mla(f32x16& p0, f32x16& p1, float& m_reg, f32x16& negm, float& alpha) {
;     constexpr float THRL = THR * LOG2E;
;     float pmax = p0[0];
; #pragma unroll
;     for (int r = 1; r < 16; ++r) pmax = fmaxf(pmax, p0[r]);
; #pragma unroll
;     for (int r = 0; r < 16; ++r) pmax = fmaxf(pmax, p1[r]);
;     { auto rr = __builtin_amdgcn_permlane32_swap(__float_as_uint(pmax), __float_as_uint(pmax), false, false);
;       pmax = fmaxf(__uint_as_float(rr[0]), __uint_as_float(rr[1])); }
;     if (!FIRST && __builtin_expect(__all(pmax <= THRL), 1)) { alpha = 1.f; }
;     else { const float dl = FIRST ? pmax : fmaxf(pmax, 0.f); m_reg += dl; alpha = FIRST ? 1.f : __builtin_amdgcn_exp2f(-dl);
; #pragma unroll
;         for (int r = 0; r < 16; ++r) { p0[r] -= dl; p1[r] -= dl; }
; #pragma unroll
;         for (int r = 0; r < 16; ++r) negm[r] = -m_reg;
;         asm volatile("" : "+v"(negm)); }
; #pragma unroll
;     for (int r = 0; r < 16; ++r) p0[r] = __builtin_amdgcn_exp2f(p0[r]);
; }
; template <int OFF> __device__ __forceinline__ s16x4 tr_read(int vb) {
;     s16x4 r; asm volatile("ds_read_b64_tr_b16 %0, %1 offset:%2" : "=&v"(r) : "v"(vb), "i"(OFF) : "memory"); return r;
; }
; template <int KS> __device__ __forceinline__ void pv_ks(f32x16* o, int vb, bf16x8 pa) {
;     const s16x4 l0 = tr_read<v_rd_off(0, KS, 0)>(vb), h0 = tr_read<v_rd_off(0, KS, 1)>(vb), l1 = tr_read<v_rd_off(1, KS, 0)>(vb), h1 = tr_read<v_rd_off(1, KS, 1)>(vb);
;     const s16x4 l2 = tr_read<v_rd_off(2, KS, 0)>(vb), h2 = tr_read<v_rd_off(2, KS, 1)>(vb), l3 = tr_read<v_rd_off(3, KS, 0)>(vb), h3 = tr_read<v_rd_off(3, KS, 1)>(vb);
;     asm volatile("s_waitcnt lgkmcnt(0)" ::: "memory"); SBAR();
;     ...
;     o[0] = __builtin_amdgcn_mfma_f32_32x32x16_bf16(pa, PK(l0, h0), o[0], 0, 0, 0);
;     o[1] = __builtin_amdgcn_mfma_f32_32x32x16_bf16(pa, PK(l1, h1), o[1], 0, 0, 0);
;     o[2] = __builtin_amdgcn_mfma_f32_32x32x16_bf16(pa, PK(l2, h2), o[2], 0, 0, 0);
;     o[3] = __builtin_amdgcn_mfma_f32_32x32x16_bf16(pa, PK(l3, h3), o[3], 0, 0, 0);
	v_mfma_f32_32x32x16_bf16 v[0:15], v[180:183], v[106:109], v[0:15]
	ds_read_b64_tr_b16 v[106:107], v110 offset:0x1400
	ds_read_b64_tr_b16 v[108:109], v110 offset:0x1c00
	v_max3_f32 v111, v111, v80, v81
	v_max3_f32 v111, v111, v82, v83
	v_mfma_f32_32x32x16_bf16 v[48:63], v[180:183], v[188:191], v[48:63]
	ds_read_b64_tr_b16 v[188:189], v110 offset:0x1600
	ds_read_b64_tr_b16 v[190:191], v110 offset:0x1e00
	v_max3_f32 v111, v111, v84, v85
	v_max3_f32 v111, v111, v86, v87
	v_mfma_f32_32x32x16_bf16 v[32:47], v[180:183], v[246:249], v[32:47]
	v_max3_f32 v111, v111, v88, v89
	v_max3_f32 v111, v111, v90, v91
	v_mfma_f32_32x32x16_bf16 v[16:31], v[180:183], v[206:209], v[16:31]
	ds_read_b64_tr_b16 v[246:247], v110 offset:0x2000
	ds_read_b64_tr_b16 v[248:249], v110 offset:0x2800
	ds_read_b64_tr_b16 v[206:207], v110 offset:0x2200
	ds_read_b64_tr_b16 v[208:209], v110 offset:0x2a00
	v_max3_f32 v111, v111, v92, v93
	v_max3_f32 v111, v111, v94, v95
	v_mov_b32_e32 v245, v111
	s_waitcnt lgkmcnt(4)
	v_mfma_f32_32x32x16_bf16 v[0:15], v[176:179], v[228:231], v[0:15]
	ds_read_b64_tr_b16 v[228:229], v110 offset:0x2400
	ds_read_b64_tr_b16 v[230:231], v110 offset:0x2c00
	v_permlane32_swap_b32_e32 v111, v245
	v_mfma_f32_32x32x16_bf16 v[48:63], v[176:179], v[236:239], v[48:63]
	ds_read_b64_tr_b16 v[236:237], v110 offset:0x2600
	ds_read_b64_tr_b16 v[238:239], v110 offset:0x2e00
	v_max_f32_e32 v245, v245, v245
	v_max_f32_e32 v111, v111, v111
	v_max_f32_e32 v111, v111, v245
	v_mfma_f32_32x32x16_bf16 v[32:47], v[176:179], v[106:109], v[32:47]
	v_cmp_ge_f32_e32 vcc, s90, v111
	s_cmp_eq_u64 vcc, exec
	v_mov_b32_e32 v243, 1.0
	v_mfma_f32_32x32x16_bf16 v[16:31], v[176:179], v[188:191], v[16:31]
	ds_read_b64_tr_b16 v[106:107], v110 offset:0x3000
	ds_read_b64_tr_b16 v[108:109], v110 offset:0x3800
	ds_read_b64_tr_b16 v[188:189], v110 offset:0x3200
	ds_read_b64_tr_b16 v[190:191], v110 offset:0x3a00
	s_cbranch_scc0 .LBB0_483
.LBB0_468:
	v_exp_f32_e32 v112, v112
	v_exp_f32_e32 v113, v113
	v_exp_f32_e32 v114, v114
	v_exp_f32_e32 v115, v115
	s_waitcnt lgkmcnt(4)
	v_mfma_f32_32x32x16_bf16 v[0:15], v[96:99], v[246:249], v[0:15]
	ds_read_b64_tr_b16 v[246:247], v110 offset:0x3400
	ds_read_b64_tr_b16 v[248:249], v110 offset:0x3c00
	v_exp_f32_e32 v116, v116
	v_exp_f32_e32 v117, v117
	v_cvt_pk_bf16_f32 v180, v112, v113
	v_mfma_f32_32x32x16_bf16 v[48:63], v[96:99], v[206:209], v[48:63]
	ds_read_b64_tr_b16 v[206:207], v110 offset:0x3600
	ds_read_b64_tr_b16 v[208:209], v110 offset:0x3e00
	v_exp_f32_e32 v118, v118
	v_exp_f32_e32 v119, v119
	v_cvt_pk_bf16_f32 v181, v114, v115
	v_mfma_f32_32x32x16_bf16 v[32:47], v[96:99], v[228:231], v[32:47]
	v_exp_f32_e32 v120, v120
	v_exp_f32_e32 v121, v121
	v_cvt_pk_bf16_f32 v182, v116, v117
	v_mfma_f32_32x32x16_bf16 v[16:31], v[96:99], v[236:239], v[16:31]
	v_exp_f32_e32 v122, v122
	v_exp_f32_e32 v123, v123
	v_cvt_pk_bf16_f32 v183, v118, v119
	v_add_f32_e32 v186, v113, v112
	s_waitcnt lgkmcnt(0)
	v_mfma_f32_32x32x16_bf16 v[0:15], v[102:105], v[106:109], v[0:15]
	v_exp_f32_e32 v124, v124
	v_exp_f32_e32 v125, v125
	v_permlane32_swap_b32_e32 v180, v182
	v_add_f32_e32 v186, v114, v186
	v_add_f32_e32 v186, v115, v186
	v_mfma_f32_32x32x16_bf16 v[48:63], v[102:105], v[188:191], v[48:63]
	v_exp_f32_e32 v126, v126
	v_exp_f32_e32 v127, v127
	v_permlane32_swap_b32_e32 v181, v183
	v_add_f32_e32 v186, v116, v186
	v_add_f32_e32 v186, v117, v186
	v_mfma_f32_32x32x16_bf16 v[32:47], v[102:105], v[246:249], v[32:47]
	v_cvt_pk_bf16_f32 v176, v120, v121
	v_cvt_pk_bf16_f32 v177, v122, v123
	v_cvt_pk_bf16_f32 v178, v124, v125
	v_add_f32_e32 v186, v118, v186
	v_add_f32_e32 v186, v119, v186
	v_add_f32_e32 v186, v120, v186
	v_mfma_f32_32x32x16_bf16 v[16:31], v[102:105], v[206:209], v[16:31]
	v_cvt_pk_bf16_f32 v179, v126, v127
	v_add_f32_e32 v186, v121, v186
	v_add_f32_e32 v186, v122, v186
	v_add_f32_e32 v186, v123, v186
	v_add_f32_e32 v186, v124, v186
	v_permlane32_swap_b32_e32 v176, v178
	v_add_f32_e32 v186, v125, v186
	v_permlane32_swap_b32_e32 v177, v179
	v_add_f32_e32 v186, v126, v186
	v_add_f32_e32 v186, v127, v186
	v_cmp_gt_f32_e32 vcc, 1.0, v243
	s_cbranch_vccz .LBB0_472
	s_and_saveexec_b64 s[10:11], s[36:37]
	ds_write_b32 v211, v243 offset:128
	s_or_b64 exec, exec, s[10:11]
	s_waitcnt lgkmcnt(0)
	v_add_u32_e32 v126, v193, v184
	ds_read_b128 v[114:117], v126 offset:224
	ds_read_b128 v[118:121], v126 offset:192
	ds_read_b128 v[122:125], v126 offset:160
	ds_read_b128 v[188:191], v126 offset:128
	s_waitcnt lgkmcnt(0)
	v_pk_mul_f32 v[12:13], v[12:13], v[114:115]
	v_pk_mul_f32 v[8:9], v[8:9], v[118:119]
	v_pk_mul_f32 v[4:5], v[4:5], v[122:123]
	v_pk_mul_f32 v[14:15], v[14:15], v[116:117]
	v_pk_mul_f32 v[10:11], v[10:11], v[120:121]
	v_pk_mul_f32 v[6:7], v[6:7], v[124:125]
	v_pk_mul_f32 v[2:3], v[2:3], v[190:191]
	v_pk_mul_f32 v[0:1], v[0:1], v[188:189]
	v_pk_mul_f32 v[60:61], v[60:61], v[114:115]
	v_pk_mul_f32 v[56:57], v[56:57], v[118:119]
	v_pk_mul_f32 v[52:53], v[52:53], v[122:123]
	v_pk_mul_f32 v[62:63], v[62:63], v[116:117]
	v_pk_mul_f32 v[58:59], v[58:59], v[120:121]
	v_pk_mul_f32 v[54:55], v[54:55], v[124:125]
	v_pk_mul_f32 v[50:51], v[50:51], v[190:191]
	v_pk_mul_f32 v[48:49], v[48:49], v[188:189]
	v_pk_mul_f32 v[44:45], v[44:45], v[114:115]
	v_pk_mul_f32 v[40:41], v[40:41], v[118:119]
	v_pk_mul_f32 v[36:37], v[36:37], v[122:123]
	v_pk_mul_f32 v[46:47], v[46:47], v[116:117]
	v_pk_mul_f32 v[42:43], v[42:43], v[120:121]
	v_pk_mul_f32 v[38:39], v[38:39], v[124:125]
	v_pk_mul_f32 v[34:35], v[34:35], v[190:191]
	v_pk_mul_f32 v[32:33], v[32:33], v[188:189]
	v_pk_mul_f32 v[28:29], v[28:29], v[114:115]
	v_pk_mul_f32 v[24:25], v[24:25], v[118:119]
	v_pk_mul_f32 v[20:21], v[20:21], v[122:123]
	v_pk_mul_f32 v[30:31], v[30:31], v[116:117]
	v_pk_mul_f32 v[26:27], v[26:27], v[120:121]
	v_pk_mul_f32 v[22:23], v[22:23], v[124:125]
	v_pk_mul_f32 v[18:19], v[18:19], v[190:191]
	v_pk_mul_f32 v[16:17], v[16:17], v[188:189]
